# mixer-in GEMM epilogue: specialized straight-line ID and SILU paths (no per-element scalar branching); K-mean and log-forget tiles keep generic path
# speedup vs baseline: 1.0067x; 1.0067x over previous
;     __device__ __forceinline__ void operator()(const f32x4 (&acc)[2][2][4][2], const Unit& u, int wr, int wc, int fr, int fq, int ui, PG8_LAS unsigned char* lds) const {
;         const int row0 = u.pm * BM + wr * 64 + fr, col0 = u.pn * BM + wc * 32 + 8 * fq;
;         const PG8_LAS float* tab = (const PG8_LAS float*)(lds + RSTD_TAB) + ui * 256 + wr * 64 + fr;
;         const int sec = (u.pn * BM) >> 10;
;         int act = 0; float sc = 1.f;
;         if (mode == 0) act = (sec == 0 || sec == 3) ? 1 : (sec == 1 ? 2 : 0);
;         else if (mode == 1) sc = (sec == 0) ? qscale : 1.f;
;         else act = 3;
;         const bool ksum = (mode == 1) && (sec == 1);
;         f32x4 csum[2][2] = {{(f32x4){0.f, 0.f, 0.f, 0.f}, (f32x4){0.f, 0.f, 0.f, 0.f}}, {(f32x4){0.f, 0.f, 0.f, 0.f}, (f32x4){0.f, 0.f, 0.f, 0.f}}};
; #pragma unroll
;         for (int ai = 0; ai < 2; ++ai) {
;             float rs4[4];
; #pragma unroll
;             for (int m = 0; m < 4; ++m) {
;                 if ((m & 1) == 0) {
;                     if (use_tab) { rs4[m] = tab[ai * HALF + m * 16] * sc; rs4[m + 1] = tab[ai * HALF + (m + 1) * 16] * sc; }
;                     else {
;                         asm volatile("" ::: "memory");
;                         rs4[m] = __builtin_amdgcn_rsqf(ssq_row(ssq, row0 + ai * HALF + m * 16) * (1.0f / 1024.0f) + RMS_EPS) * sc;
;                         rs4[m + 1] = __builtin_amdgcn_rsqf(ssq_row(ssq, row0 + ai * HALF + (m + 1) * 16) * (1.0f / 1024.0f) + RMS_EPS) * sc;
;                     }
;                 }
;                 const int row = row0 + ai * HALF + m * 16;
;                 const float rs = rs4[m];
;                 bf16_t* rowp = O + (size_t)row * ldc + col0;
; #pragma unroll
;                 for (int bj = 0; bj < 2; ++bj) {
;                     f32x4 v[2] = {acc[ai][bj][m][0] * rs, acc[ai][bj][m][1] * rs};
;                     if (ksum) { csum[bj][0] += v[0]; csum[bj][1] += v[1]; }
; #pragma unroll
;                     for (int n = 0; n < 2; ++n) {
;                         f32x4 lbv = (f32x4){0.f, 0.f, 0.f, 0.f};
;                         if (act == 2) lbv = *(const f32x4*)(lb + (col0 - 1024) + bj * HALF + 4 * n);
; #pragma unroll
;                         for (int e = 0; e < 4; ++e) {
;                             float x = v[n][e];
;                             if (act == 1) x = silu_f(x);
.LBB0_226:
	s_andn2_b64 vcc, exec, s[40:41]
	s_cbranch_vccnz .Lepi_generic
	s_cmp_eq_u32 s71, 1
	s_cselect_b64 s[38:39], -1, 0
	s_and_b64 s[38:39], s[38:39], s[58:59]
	s_and_b64 vcc, exec, s[38:39]
	s_cbranch_vccnz .Lepi_generic
	s_cmp_eq_u32 s48, 0
	s_cbranch_scc1 .Lepi_id
	s_cmp_eq_u32 s48, 1
	s_cbranch_scc1 .Lepi_silu
	s_branch .Lepi_generic
.Lepi_id:
	v_lshl_add_u32 v150, s78, 8, v164
	s_lshl_b32 s1, s1, 10
	v_add_u32_e32 v170, s1, v166
	ds_read_b32 v128, v170
	ds_read_b32 v130, v170 offset:64
	ds_read_b32 v144, v170 offset:128
	ds_read_b32 v146, v170 offset:192
	ds_read_b32 v148, v170 offset:512
	ds_read_b32 v156, v170 offset:576
	ds_read_b32 v158, v170 offset:640
	ds_read_b32 v160, v170 offset:704
	s_lshl_b32 s73, s0, 8
	v_or_b32_e32 v172, s73, v167
	v_mov_b32_e32 v173, 0
	v_mad_u64_u32 v[162:163], s[38:39], v150, s96, 0
	s_lshl_b32 s46, s96, 5
	s_mov_b32 s47, 0
	s_lshl_b32 s52, s96, 8
	s_mov_b32 s53, 0
	v_lshl_add_u64 v[162:163], v[162:163], 1, s[14:15]
	v_lshl_add_u64 v[162:163], v[172:173], 1, v[162:163]
	v_lshl_add_u64 v[178:179], v[162:163], 0, s[52:53]
	s_waitcnt lgkmcnt(0)
	v_mul_f32_e32 v128, v169, v128
	v_mul_f32_e32 v130, v169, v130
	v_mul_f32_e32 v144, v169, v144
	v_mul_f32_e32 v146, v169, v146
	v_mul_f32_e32 v148, v169, v148
	v_mul_f32_e32 v156, v169, v156
	v_mul_f32_e32 v158, v169, v158
	v_mul_f32_e32 v160, v169, v160
	v_pk_mul_f32 v[124:125], v[124:125], v[128:129] op_sel_hi:[1,0]
	v_pk_mul_f32 v[126:127], v[126:127], v[128:129] op_sel_hi:[1,0]
	v_pk_mul_f32 v[120:121], v[120:121], v[128:129] op_sel_hi:[1,0]
	v_pk_mul_f32 v[122:123], v[122:123], v[128:129] op_sel_hi:[1,0]
	v_cvt_pk_bf16_f32 v124, v124, v125
	v_cvt_pk_bf16_f32 v125, v126, v127
	v_cvt_pk_bf16_f32 v126, v120, v121
	v_cvt_pk_bf16_f32 v127, v122, v123
	global_store_dwordx4 v[162:163], v[124:127], off
	v_pk_mul_f32 v[116:117], v[116:117], v[128:129] op_sel_hi:[1,0]
	v_pk_mul_f32 v[118:119], v[118:119], v[128:129] op_sel_hi:[1,0]
	v_pk_mul_f32 v[112:113], v[112:113], v[128:129] op_sel_hi:[1,0]
	v_pk_mul_f32 v[114:115], v[114:115], v[128:129] op_sel_hi:[1,0]
	v_cvt_pk_bf16_f32 v116, v116, v117
	v_cvt_pk_bf16_f32 v117, v118, v119
	v_cvt_pk_bf16_f32 v118, v112, v113
	v_cvt_pk_bf16_f32 v119, v114, v115
	global_store_dwordx4 v[162:163], v[116:119], off offset:256
	v_lshl_add_u64 v[176:177], v[162:163], 0, s[46:47]
	v_pk_mul_f32 v[108:109], v[108:109], v[130:131] op_sel_hi:[1,0]
	v_pk_mul_f32 v[110:111], v[110:111], v[130:131] op_sel_hi:[1,0]
	v_pk_mul_f32 v[104:105], v[104:105], v[130:131] op_sel_hi:[1,0]
	v_pk_mul_f32 v[106:107], v[106:107], v[130:131] op_sel_hi:[1,0]
	v_cvt_pk_bf16_f32 v108, v108, v109
	v_cvt_pk_bf16_f32 v109, v110, v111
	v_cvt_pk_bf16_f32 v110, v104, v105
	v_cvt_pk_bf16_f32 v111, v106, v107
	global_store_dwordx4 v[176:177], v[108:111], off
	v_pk_mul_f32 v[100:101], v[100:101], v[130:131] op_sel_hi:[1,0]
	v_pk_mul_f32 v[102:103], v[102:103], v[130:131] op_sel_hi:[1,0]
	v_pk_mul_f32 v[96:97], v[96:97], v[130:131] op_sel_hi:[1,0]
	v_pk_mul_f32 v[98:99], v[98:99], v[130:131] op_sel_hi:[1,0]
	v_cvt_pk_bf16_f32 v100, v100, v101
	v_cvt_pk_bf16_f32 v101, v102, v103
	v_cvt_pk_bf16_f32 v102, v96, v97
	v_cvt_pk_bf16_f32 v103, v98, v99
	global_store_dwordx4 v[176:177], v[100:103], off offset:256
	v_lshl_add_u64 v[162:163], v[176:177], 0, s[46:47]
	v_pk_mul_f32 v[92:93], v[92:93], v[144:145] op_sel_hi:[1,0]
	v_pk_mul_f32 v[94:95], v[94:95], v[144:145] op_sel_hi:[1,0]
	v_pk_mul_f32 v[88:89], v[88:89], v[144:145] op_sel_hi:[1,0]
	v_pk_mul_f32 v[90:91], v[90:91], v[144:145] op_sel_hi:[1,0]
	v_cvt_pk_bf16_f32 v92, v92, v93
	v_cvt_pk_bf16_f32 v93, v94, v95
	v_cvt_pk_bf16_f32 v94, v88, v89
	v_cvt_pk_bf16_f32 v95, v90, v91
	global_store_dwordx4 v[162:163], v[92:95], off
	v_pk_mul_f32 v[84:85], v[84:85], v[144:145] op_sel_hi:[1,0]
	v_pk_mul_f32 v[86:87], v[86:87], v[144:145] op_sel_hi:[1,0]
	v_pk_mul_f32 v[80:81], v[80:81], v[144:145] op_sel_hi:[1,0]
	v_pk_mul_f32 v[82:83], v[82:83], v[144:145] op_sel_hi:[1,0]
	v_cvt_pk_bf16_f32 v84, v84, v85
	v_cvt_pk_bf16_f32 v85, v86, v87
	v_cvt_pk_bf16_f32 v86, v80, v81
	v_cvt_pk_bf16_f32 v87, v82, v83
	global_store_dwordx4 v[162:163], v[84:87], off offset:256
	v_lshl_add_u64 v[176:177], v[162:163], 0, s[46:47]
	v_pk_mul_f32 v[76:77], v[76:77], v[146:147] op_sel_hi:[1,0]
	v_pk_mul_f32 v[78:79], v[78:79], v[146:147] op_sel_hi:[1,0]
	v_pk_mul_f32 v[72:73], v[72:73], v[146:147] op_sel_hi:[1,0]
	v_pk_mul_f32 v[74:75], v[74:75], v[146:147] op_sel_hi:[1,0]
	v_cvt_pk_bf16_f32 v76, v76, v77
	v_cvt_pk_bf16_f32 v77, v78, v79
	v_cvt_pk_bf16_f32 v78, v72, v73
	v_cvt_pk_bf16_f32 v79, v74, v75
	global_store_dwordx4 v[176:177], v[76:79], off
	v_pk_mul_f32 v[68:69], v[68:69], v[146:147] op_sel_hi:[1,0]
	v_pk_mul_f32 v[70:71], v[70:71], v[146:147] op_sel_hi:[1,0]
	v_pk_mul_f32 v[64:65], v[64:65], v[146:147] op_sel_hi:[1,0]
	v_pk_mul_f32 v[66:67], v[66:67], v[146:147] op_sel_hi:[1,0]
	v_cvt_pk_bf16_f32 v68, v68, v69
	v_cvt_pk_bf16_f32 v69, v70, v71
	v_cvt_pk_bf16_f32 v70, v64, v65
	v_cvt_pk_bf16_f32 v71, v66, v67
	global_store_dwordx4 v[176:177], v[68:71], off offset:256
	v_lshl_add_u64 v[162:163], v[178:179], 0, 0
	v_pk_mul_f32 v[60:61], v[60:61], v[148:149] op_sel_hi:[1,0]
	v_pk_mul_f32 v[62:63], v[62:63], v[148:149] op_sel_hi:[1,0]
	v_pk_mul_f32 v[56:57], v[56:57], v[148:149] op_sel_hi:[1,0]
	v_pk_mul_f32 v[58:59], v[58:59], v[148:149] op_sel_hi:[1,0]
	v_cvt_pk_bf16_f32 v60, v60, v61
	v_cvt_pk_bf16_f32 v61, v62, v63
	v_cvt_pk_bf16_f32 v62, v56, v57
	v_cvt_pk_bf16_f32 v63, v58, v59
	global_store_dwordx4 v[162:163], v[60:63], off
	v_pk_mul_f32 v[52:53], v[52:53], v[148:149] op_sel_hi:[1,0]
	v_pk_mul_f32 v[54:55], v[54:55], v[148:149] op_sel_hi:[1,0]
; __device__ __forceinline__ unsigned cvt_pk_bf16(float lo, float hi) { unsigned r; asm volatile("v_cvt_pk_bf16_f32 %0, %1, %2" : "=v"(r) : "v"(lo), "v"(hi)); return r; }
; __device__ __forceinline__ float silu_f(float v) { return v * __builtin_amdgcn_rcpf(1.f + __expf(-v)); }
;     __device__ __forceinline__ void operator()(const f32x4 (&acc)[2][2][4][2], const Unit& u, int wr, int wc, int fr, int fq, int ui, PG8_LAS unsigned char* lds) const {
;     ...
;                 const int row = row0 + ai * HALF + m * 16;
;                 const float rs = rs4[m];
;                 bf16_t* rowp = O + (size_t)row * ldc + col0;
; #pragma unroll
;                 for (int bj = 0; bj < 2; ++bj) {
;                     f32x4 v[2] = {acc[ai][bj][m][0] * rs, acc[ai][bj][m][1] * rs};
;                     if (ksum) { csum[bj][0] += v[0]; csum[bj][1] += v[1]; }
; #pragma unroll
;                     for (int n = 0; n < 2; ++n) {
;                         f32x4 lbv = (f32x4){0.f, 0.f, 0.f, 0.f};
;                         if (act == 2) lbv = *(const f32x4*)(lb + (col0 - 1024) + bj * HALF + 4 * n);
; #pragma unroll
;                         for (int e = 0; e < 4; ++e) {
;                             float x = v[n][e];
;                             if (act == 1) x = silu_f(x);
;                             else if (act == 2) { const float l = lbv[e]; x = __logf(l + (1.f - l) * __builtin_amdgcn_rcpf(1.f + __expf(-x))); }
;                             else if (act == 3) { x = fmaxf(x, 0.f); x = x * x; }
;                             v[n][e] = x;
;                         }
;                     }
;                     u32x4 w; w.x = cvt_pk_bf16(v[0][0], v[0][1]); w.y = cvt_pk_bf16(v[0][2], v[0][3]); w.z = cvt_pk_bf16(v[1][0], v[1][1]); w.w = cvt_pk_bf16(v[1][2], v[1][3]);
;                     *(u32x4*)(rowp + bj * HALF) = w;
	v_pk_mul_f32 v[48:49], v[48:49], v[148:149] op_sel_hi:[1,0]
	v_pk_mul_f32 v[50:51], v[50:51], v[148:149] op_sel_hi:[1,0]
	v_cvt_pk_bf16_f32 v52, v52, v53
	v_cvt_pk_bf16_f32 v53, v54, v55
	v_cvt_pk_bf16_f32 v54, v48, v49
	v_cvt_pk_bf16_f32 v55, v50, v51
	global_store_dwordx4 v[162:163], v[52:55], off offset:256
	v_lshl_add_u64 v[176:177], v[162:163], 0, s[46:47]
	v_pk_mul_f32 v[44:45], v[44:45], v[156:157] op_sel_hi:[1,0]
	v_pk_mul_f32 v[46:47], v[46:47], v[156:157] op_sel_hi:[1,0]
	v_pk_mul_f32 v[40:41], v[40:41], v[156:157] op_sel_hi:[1,0]
	v_pk_mul_f32 v[42:43], v[42:43], v[156:157] op_sel_hi:[1,0]
	v_cvt_pk_bf16_f32 v44, v44, v45
	v_cvt_pk_bf16_f32 v45, v46, v47
	v_cvt_pk_bf16_f32 v46, v40, v41
	v_cvt_pk_bf16_f32 v47, v42, v43
	global_store_dwordx4 v[176:177], v[44:47], off
	v_pk_mul_f32 v[36:37], v[36:37], v[156:157] op_sel_hi:[1,0]
	v_pk_mul_f32 v[38:39], v[38:39], v[156:157] op_sel_hi:[1,0]
	v_pk_mul_f32 v[32:33], v[32:33], v[156:157] op_sel_hi:[1,0]
	v_pk_mul_f32 v[34:35], v[34:35], v[156:157] op_sel_hi:[1,0]
	v_cvt_pk_bf16_f32 v36, v36, v37
	v_cvt_pk_bf16_f32 v37, v38, v39
	v_cvt_pk_bf16_f32 v38, v32, v33
	v_cvt_pk_bf16_f32 v39, v34, v35
	global_store_dwordx4 v[176:177], v[36:39], off offset:256
	v_lshl_add_u64 v[162:163], v[176:177], 0, s[46:47]
	v_pk_mul_f32 v[28:29], v[28:29], v[158:159] op_sel_hi:[1,0]
	v_pk_mul_f32 v[30:31], v[30:31], v[158:159] op_sel_hi:[1,0]
	v_pk_mul_f32 v[24:25], v[24:25], v[158:159] op_sel_hi:[1,0]
	v_pk_mul_f32 v[26:27], v[26:27], v[158:159] op_sel_hi:[1,0]
	v_cvt_pk_bf16_f32 v28, v28, v29
	v_cvt_pk_bf16_f32 v29, v30, v31
	v_cvt_pk_bf16_f32 v30, v24, v25
	v_cvt_pk_bf16_f32 v31, v26, v27
	global_store_dwordx4 v[162:163], v[28:31], off
	v_pk_mul_f32 v[20:21], v[20:21], v[158:159] op_sel_hi:[1,0]
	v_pk_mul_f32 v[22:23], v[22:23], v[158:159] op_sel_hi:[1,0]
	v_pk_mul_f32 v[16:17], v[16:17], v[158:159] op_sel_hi:[1,0]
	v_pk_mul_f32 v[18:19], v[18:19], v[158:159] op_sel_hi:[1,0]
	v_cvt_pk_bf16_f32 v20, v20, v21
	v_cvt_pk_bf16_f32 v21, v22, v23
	v_cvt_pk_bf16_f32 v22, v16, v17
	v_cvt_pk_bf16_f32 v23, v18, v19
	global_store_dwordx4 v[162:163], v[20:23], off offset:256
	v_lshl_add_u64 v[176:177], v[162:163], 0, s[46:47]
	v_pk_mul_f32 v[12:13], v[12:13], v[160:161] op_sel_hi:[1,0]
	v_pk_mul_f32 v[14:15], v[14:15], v[160:161] op_sel_hi:[1,0]
	v_pk_mul_f32 v[8:9], v[8:9], v[160:161] op_sel_hi:[1,0]
	v_pk_mul_f32 v[10:11], v[10:11], v[160:161] op_sel_hi:[1,0]
	v_cvt_pk_bf16_f32 v12, v12, v13
	v_cvt_pk_bf16_f32 v13, v14, v15
	v_cvt_pk_bf16_f32 v14, v8, v9
	v_cvt_pk_bf16_f32 v15, v10, v11
	global_store_dwordx4 v[176:177], v[12:15], off
	v_pk_mul_f32 v[4:5], v[4:5], v[160:161] op_sel_hi:[1,0]
	v_pk_mul_f32 v[6:7], v[6:7], v[160:161] op_sel_hi:[1,0]
	v_pk_mul_f32 v[0:1], v[0:1], v[160:161] op_sel_hi:[1,0]
	v_pk_mul_f32 v[2:3], v[2:3], v[160:161] op_sel_hi:[1,0]
	v_cvt_pk_bf16_f32 v4, v4, v5
	v_cvt_pk_bf16_f32 v5, v6, v7
	v_cvt_pk_bf16_f32 v6, v0, v1
	v_cvt_pk_bf16_f32 v7, v2, v3
	global_store_dwordx4 v[176:177], v[4:7], off offset:256
	s_branch .LBB0_1108
.Lepi_silu:
	v_lshl_add_u32 v150, s78, 8, v164
	s_lshl_b32 s1, s1, 10
	v_add_u32_e32 v170, s1, v166
	ds_read_b32 v128, v170
	ds_read_b32 v130, v170 offset:64
	ds_read_b32 v144, v170 offset:128
	ds_read_b32 v146, v170 offset:192
	ds_read_b32 v148, v170 offset:512
	ds_read_b32 v156, v170 offset:576
	ds_read_b32 v158, v170 offset:640
	ds_read_b32 v160, v170 offset:704
	s_lshl_b32 s73, s0, 8
	v_or_b32_e32 v172, s73, v167
	v_mov_b32_e32 v173, 0
	v_mad_u64_u32 v[162:163], s[38:39], v150, s96, 0
	s_lshl_b32 s46, s96, 5
	s_mov_b32 s47, 0
	s_lshl_b32 s52, s96, 8
	s_mov_b32 s53, 0
	v_lshl_add_u64 v[162:163], v[162:163], 1, s[14:15]
	v_lshl_add_u64 v[162:163], v[172:173], 1, v[162:163]
	v_lshl_add_u64 v[178:179], v[162:163], 0, s[52:53]
	s_waitcnt lgkmcnt(0)
	v_mul_f32_e32 v128, v169, v128
	v_mul_f32_e32 v130, v169, v130
	v_mul_f32_e32 v144, v169, v144
	v_mul_f32_e32 v146, v169, v146
	v_mul_f32_e32 v148, v169, v148
	v_mul_f32_e32 v156, v169, v156
	v_mul_f32_e32 v158, v169, v158
	v_mul_f32_e32 v160, v169, v160
	v_pk_mul_f32 v[124:125], v[124:125], v[128:129] op_sel_hi:[1,0]
	v_pk_mul_f32 v[126:127], v[126:127], v[128:129] op_sel_hi:[1,0]
	v_pk_mul_f32 v[120:121], v[120:121], v[128:129] op_sel_hi:[1,0]
	v_pk_mul_f32 v[122:123], v[122:123], v[128:129] op_sel_hi:[1,0]
	v_mul_f32_e32 v184, 0xbfb8aa3b, v124
	v_mul_f32_e32 v185, 0xbfb8aa3b, v125
	v_mul_f32_e32 v186, 0xbfb8aa3b, v126
	v_mul_f32_e32 v187, 0xbfb8aa3b, v127
	v_mul_f32_e32 v188, 0xbfb8aa3b, v120
	v_mul_f32_e32 v189, 0xbfb8aa3b, v121
	v_mul_f32_e32 v190, 0xbfb8aa3b, v122
	v_mul_f32_e32 v191, 0xbfb8aa3b, v123
	v_exp_f32_e32 v184, v184
	v_exp_f32_e32 v185, v185
	v_exp_f32_e32 v186, v186
	v_exp_f32_e32 v187, v187
	v_exp_f32_e32 v188, v188
	v_exp_f32_e32 v189, v189
	v_exp_f32_e32 v190, v190
	v_exp_f32_e32 v191, v191
	v_add_f32_e32 v184, 1.0, v184
	v_add_f32_e32 v185, 1.0, v185
	v_add_f32_e32 v186, 1.0, v186
	v_add_f32_e32 v187, 1.0, v187
	v_add_f32_e32 v188, 1.0, v188
	v_add_f32_e32 v189, 1.0, v189
	v_add_f32_e32 v190, 1.0, v190
	v_add_f32_e32 v191, 1.0, v191
	v_rcp_f32_e32 v184, v184
	v_rcp_f32_e32 v185, v185
	v_rcp_f32_e32 v186, v186
	v_rcp_f32_e32 v187, v187
	v_rcp_f32_e32 v188, v188
	v_rcp_f32_e32 v189, v189
	v_rcp_f32_e32 v190, v190
	v_rcp_f32_e32 v191, v191
	v_mul_f32_e32 v124, v124, v184
	v_mul_f32_e32 v125, v125, v185
	v_mul_f32_e32 v126, v126, v186
	v_mul_f32_e32 v127, v127, v187
	v_mul_f32_e32 v120, v120, v188
	v_mul_f32_e32 v121, v121, v189
	v_mul_f32_e32 v122, v122, v190
	v_mul_f32_e32 v123, v123, v191
	v_cvt_pk_bf16_f32 v124, v124, v125
	v_cvt_pk_bf16_f32 v125, v126, v127
	v_cvt_pk_bf16_f32 v126, v120, v121
; __device__ __forceinline__ unsigned cvt_pk_bf16(float lo, float hi) { unsigned r; asm volatile("v_cvt_pk_bf16_f32 %0, %1, %2" : "=v"(r) : "v"(lo), "v"(hi)); return r; }
; __device__ __forceinline__ float silu_f(float v) { return v * __builtin_amdgcn_rcpf(1.f + __expf(-v)); }
;     __device__ __forceinline__ void operator()(const f32x4 (&acc)[2][2][4][2], const Unit& u, int wr, int wc, int fr, int fq, int ui, PG8_LAS unsigned char* lds) const {
;     ...
;                 const int row = row0 + ai * HALF + m * 16;
;                 const float rs = rs4[m];
;                 bf16_t* rowp = O + (size_t)row * ldc + col0;
; #pragma unroll
;                 for (int bj = 0; bj < 2; ++bj) {
;                     f32x4 v[2] = {acc[ai][bj][m][0] * rs, acc[ai][bj][m][1] * rs};
;                     if (ksum) { csum[bj][0] += v[0]; csum[bj][1] += v[1]; }
; #pragma unroll
;                     for (int n = 0; n < 2; ++n) {
;                         f32x4 lbv = (f32x4){0.f, 0.f, 0.f, 0.f};
;                         if (act == 2) lbv = *(const f32x4*)(lb + (col0 - 1024) + bj * HALF + 4 * n);
; #pragma unroll
;                         for (int e = 0; e < 4; ++e) {
;                             float x = v[n][e];
;                             if (act == 1) x = silu_f(x);
;                             else if (act == 2) { const float l = lbv[e]; x = __logf(l + (1.f - l) * __builtin_amdgcn_rcpf(1.f + __expf(-x))); }
;                             else if (act == 3) { x = fmaxf(x, 0.f); x = x * x; }
;                             v[n][e] = x;
;                         }
;                     }
;                     u32x4 w; w.x = cvt_pk_bf16(v[0][0], v[0][1]); w.y = cvt_pk_bf16(v[0][2], v[0][3]); w.z = cvt_pk_bf16(v[1][0], v[1][1]); w.w = cvt_pk_bf16(v[1][2], v[1][3]);
;                     *(u32x4*)(rowp + bj * HALF) = w;
	v_cvt_pk_bf16_f32 v127, v122, v123
	global_store_dwordx4 v[162:163], v[124:127], off
	v_pk_mul_f32 v[116:117], v[116:117], v[128:129] op_sel_hi:[1,0]
	v_pk_mul_f32 v[118:119], v[118:119], v[128:129] op_sel_hi:[1,0]
	v_pk_mul_f32 v[112:113], v[112:113], v[128:129] op_sel_hi:[1,0]
	v_pk_mul_f32 v[114:115], v[114:115], v[128:129] op_sel_hi:[1,0]
	v_mul_f32_e32 v184, 0xbfb8aa3b, v116
	v_mul_f32_e32 v185, 0xbfb8aa3b, v117
	v_mul_f32_e32 v186, 0xbfb8aa3b, v118
	v_mul_f32_e32 v187, 0xbfb8aa3b, v119
	v_mul_f32_e32 v188, 0xbfb8aa3b, v112
	v_mul_f32_e32 v189, 0xbfb8aa3b, v113
	v_mul_f32_e32 v190, 0xbfb8aa3b, v114
	v_mul_f32_e32 v191, 0xbfb8aa3b, v115
	v_exp_f32_e32 v184, v184
	v_exp_f32_e32 v185, v185
	v_exp_f32_e32 v186, v186
	v_exp_f32_e32 v187, v187
	v_exp_f32_e32 v188, v188
	v_exp_f32_e32 v189, v189
	v_exp_f32_e32 v190, v190
	v_exp_f32_e32 v191, v191
	v_add_f32_e32 v184, 1.0, v184
	v_add_f32_e32 v185, 1.0, v185
	v_add_f32_e32 v186, 1.0, v186
	v_add_f32_e32 v187, 1.0, v187
	v_add_f32_e32 v188, 1.0, v188
	v_add_f32_e32 v189, 1.0, v189
	v_add_f32_e32 v190, 1.0, v190
	v_add_f32_e32 v191, 1.0, v191
	v_rcp_f32_e32 v184, v184
	v_rcp_f32_e32 v185, v185
	v_rcp_f32_e32 v186, v186
	v_rcp_f32_e32 v187, v187
	v_rcp_f32_e32 v188, v188
	v_rcp_f32_e32 v189, v189
	v_rcp_f32_e32 v190, v190
	v_rcp_f32_e32 v191, v191
	v_mul_f32_e32 v116, v116, v184
	v_mul_f32_e32 v117, v117, v185
	v_mul_f32_e32 v118, v118, v186
	v_mul_f32_e32 v119, v119, v187
	v_mul_f32_e32 v112, v112, v188
	v_mul_f32_e32 v113, v113, v189
	v_mul_f32_e32 v114, v114, v190
	v_mul_f32_e32 v115, v115, v191
	v_cvt_pk_bf16_f32 v116, v116, v117
	v_cvt_pk_bf16_f32 v117, v118, v119
	v_cvt_pk_bf16_f32 v118, v112, v113
	v_cvt_pk_bf16_f32 v119, v114, v115
	global_store_dwordx4 v[162:163], v[116:119], off offset:256
	v_lshl_add_u64 v[176:177], v[162:163], 0, s[46:47]
	v_pk_mul_f32 v[108:109], v[108:109], v[130:131] op_sel_hi:[1,0]
	v_pk_mul_f32 v[110:111], v[110:111], v[130:131] op_sel_hi:[1,0]
	v_pk_mul_f32 v[104:105], v[104:105], v[130:131] op_sel_hi:[1,0]
	v_pk_mul_f32 v[106:107], v[106:107], v[130:131] op_sel_hi:[1,0]
	v_mul_f32_e32 v184, 0xbfb8aa3b, v108
	v_mul_f32_e32 v185, 0xbfb8aa3b, v109
	v_mul_f32_e32 v186, 0xbfb8aa3b, v110
	v_mul_f32_e32 v187, 0xbfb8aa3b, v111
	v_mul_f32_e32 v188, 0xbfb8aa3b, v104
	v_mul_f32_e32 v189, 0xbfb8aa3b, v105
	v_mul_f32_e32 v190, 0xbfb8aa3b, v106
	v_mul_f32_e32 v191, 0xbfb8aa3b, v107
	v_exp_f32_e32 v184, v184
	v_exp_f32_e32 v185, v185
	v_exp_f32_e32 v186, v186
	v_exp_f32_e32 v187, v187
	v_exp_f32_e32 v188, v188
	v_exp_f32_e32 v189, v189
	v_exp_f32_e32 v190, v190
	v_exp_f32_e32 v191, v191
	v_add_f32_e32 v184, 1.0, v184
	v_add_f32_e32 v185, 1.0, v185
	v_add_f32_e32 v186, 1.0, v186
	v_add_f32_e32 v187, 1.0, v187
	v_add_f32_e32 v188, 1.0, v188
	v_add_f32_e32 v189, 1.0, v189
	v_add_f32_e32 v190, 1.0, v190
	v_add_f32_e32 v191, 1.0, v191
	v_rcp_f32_e32 v184, v184
	v_rcp_f32_e32 v185, v185
	v_rcp_f32_e32 v186, v186
	v_rcp_f32_e32 v187, v187
	v_rcp_f32_e32 v188, v188
	v_rcp_f32_e32 v189, v189
	v_rcp_f32_e32 v190, v190
	v_rcp_f32_e32 v191, v191
	v_mul_f32_e32 v108, v108, v184
	v_mul_f32_e32 v109, v109, v185
	v_mul_f32_e32 v110, v110, v186
	v_mul_f32_e32 v111, v111, v187
	v_mul_f32_e32 v104, v104, v188
	v_mul_f32_e32 v105, v105, v189
	v_mul_f32_e32 v106, v106, v190
	v_mul_f32_e32 v107, v107, v191
	v_cvt_pk_bf16_f32 v108, v108, v109
	v_cvt_pk_bf16_f32 v109, v110, v111
	v_cvt_pk_bf16_f32 v110, v104, v105
	v_cvt_pk_bf16_f32 v111, v106, v107
	global_store_dwordx4 v[176:177], v[108:111], off
	v_pk_mul_f32 v[100:101], v[100:101], v[130:131] op_sel_hi:[1,0]
	v_pk_mul_f32 v[102:103], v[102:103], v[130:131] op_sel_hi:[1,0]
	v_pk_mul_f32 v[96:97], v[96:97], v[130:131] op_sel_hi:[1,0]
	v_pk_mul_f32 v[98:99], v[98:99], v[130:131] op_sel_hi:[1,0]
	v_mul_f32_e32 v184, 0xbfb8aa3b, v100
	v_mul_f32_e32 v185, 0xbfb8aa3b, v101
	v_mul_f32_e32 v186, 0xbfb8aa3b, v102
	v_mul_f32_e32 v187, 0xbfb8aa3b, v103
	v_mul_f32_e32 v188, 0xbfb8aa3b, v96
	v_mul_f32_e32 v189, 0xbfb8aa3b, v97
	v_mul_f32_e32 v190, 0xbfb8aa3b, v98
	v_mul_f32_e32 v191, 0xbfb8aa3b, v99
	v_exp_f32_e32 v184, v184
	v_exp_f32_e32 v185, v185
	v_exp_f32_e32 v186, v186
	v_exp_f32_e32 v187, v187
	v_exp_f32_e32 v188, v188
	v_exp_f32_e32 v189, v189
	v_exp_f32_e32 v190, v190
	v_exp_f32_e32 v191, v191
	v_add_f32_e32 v184, 1.0, v184
	v_add_f32_e32 v185, 1.0, v185
	v_add_f32_e32 v186, 1.0, v186
	v_add_f32_e32 v187, 1.0, v187
	v_add_f32_e32 v188, 1.0, v188
	v_add_f32_e32 v189, 1.0, v189
	v_add_f32_e32 v190, 1.0, v190
	v_add_f32_e32 v191, 1.0, v191
	v_rcp_f32_e32 v184, v184
	v_rcp_f32_e32 v185, v185
	v_rcp_f32_e32 v186, v186
	v_rcp_f32_e32 v187, v187
	v_rcp_f32_e32 v188, v188
	v_rcp_f32_e32 v189, v189
	v_rcp_f32_e32 v190, v190
	v_rcp_f32_e32 v191, v191
	v_mul_f32_e32 v100, v100, v184
	v_mul_f32_e32 v101, v101, v185
	v_mul_f32_e32 v102, v102, v186
	v_mul_f32_e32 v103, v103, v187
	v_mul_f32_e32 v96, v96, v188
	v_mul_f32_e32 v97, v97, v189
	v_mul_f32_e32 v98, v98, v190
	v_mul_f32_e32 v99, v99, v191
	v_cvt_pk_bf16_f32 v100, v100, v101
	v_cvt_pk_bf16_f32 v101, v102, v103
	v_cvt_pk_bf16_f32 v102, v96, v97
	v_cvt_pk_bf16_f32 v103, v98, v99
	global_store_dwordx4 v[176:177], v[100:103], off offset:256
	v_lshl_add_u64 v[162:163], v[176:177], 0, s[46:47]
	v_pk_mul_f32 v[92:93], v[92:93], v[144:145] op_sel_hi:[1,0]
	v_pk_mul_f32 v[94:95], v[94:95], v[144:145] op_sel_hi:[1,0]
	v_pk_mul_f32 v[88:89], v[88:89], v[144:145] op_sel_hi:[1,0]
	v_pk_mul_f32 v[90:91], v[90:91], v[144:145] op_sel_hi:[1,0]
	v_mul_f32_e32 v184, 0xbfb8aa3b, v92
	v_mul_f32_e32 v185, 0xbfb8aa3b, v93
	v_mul_f32_e32 v186, 0xbfb8aa3b, v94
	v_mul_f32_e32 v187, 0xbfb8aa3b, v95
	v_mul_f32_e32 v188, 0xbfb8aa3b, v88
; __device__ __forceinline__ unsigned cvt_pk_bf16(float lo, float hi) { unsigned r; asm volatile("v_cvt_pk_bf16_f32 %0, %1, %2" : "=v"(r) : "v"(lo), "v"(hi)); return r; }
; __device__ __forceinline__ float silu_f(float v) { return v * __builtin_amdgcn_rcpf(1.f + __expf(-v)); }
;     __device__ __forceinline__ void operator()(const f32x4 (&acc)[2][2][4][2], const Unit& u, int wr, int wc, int fr, int fq, int ui, PG8_LAS unsigned char* lds) const {
;     ...
;                 const int row = row0 + ai * HALF + m * 16;
;                 const float rs = rs4[m];
;                 bf16_t* rowp = O + (size_t)row * ldc + col0;
; #pragma unroll
;                 for (int bj = 0; bj < 2; ++bj) {
;                     f32x4 v[2] = {acc[ai][bj][m][0] * rs, acc[ai][bj][m][1] * rs};
;                     if (ksum) { csum[bj][0] += v[0]; csum[bj][1] += v[1]; }
; #pragma unroll
;                     for (int n = 0; n < 2; ++n) {
;                         f32x4 lbv = (f32x4){0.f, 0.f, 0.f, 0.f};
;                         if (act == 2) lbv = *(const f32x4*)(lb + (col0 - 1024) + bj * HALF + 4 * n);
; #pragma unroll
;                         for (int e = 0; e < 4; ++e) {
;                             float x = v[n][e];
;                             if (act == 1) x = silu_f(x);
;                             else if (act == 2) { const float l = lbv[e]; x = __logf(l + (1.f - l) * __builtin_amdgcn_rcpf(1.f + __expf(-x))); }
;                             else if (act == 3) { x = fmaxf(x, 0.f); x = x * x; }
;                             v[n][e] = x;
;                         }
;                     }
;                     u32x4 w; w.x = cvt_pk_bf16(v[0][0], v[0][1]); w.y = cvt_pk_bf16(v[0][2], v[0][3]); w.z = cvt_pk_bf16(v[1][0], v[1][1]); w.w = cvt_pk_bf16(v[1][2], v[1][3]);
;                     *(u32x4*)(rowp + bj * HALF) = w;
	v_mul_f32_e32 v189, 0xbfb8aa3b, v89
	v_mul_f32_e32 v190, 0xbfb8aa3b, v90
	v_mul_f32_e32 v191, 0xbfb8aa3b, v91
	v_exp_f32_e32 v184, v184
	v_exp_f32_e32 v185, v185
	v_exp_f32_e32 v186, v186
	v_exp_f32_e32 v187, v187
	v_exp_f32_e32 v188, v188
	v_exp_f32_e32 v189, v189
	v_exp_f32_e32 v190, v190
	v_exp_f32_e32 v191, v191
	v_add_f32_e32 v184, 1.0, v184
	v_add_f32_e32 v185, 1.0, v185
	v_add_f32_e32 v186, 1.0, v186
	v_add_f32_e32 v187, 1.0, v187
	v_add_f32_e32 v188, 1.0, v188
	v_add_f32_e32 v189, 1.0, v189
	v_add_f32_e32 v190, 1.0, v190
	v_add_f32_e32 v191, 1.0, v191
	v_rcp_f32_e32 v184, v184
	v_rcp_f32_e32 v185, v185
	v_rcp_f32_e32 v186, v186
	v_rcp_f32_e32 v187, v187
	v_rcp_f32_e32 v188, v188
	v_rcp_f32_e32 v189, v189
	v_rcp_f32_e32 v190, v190
	v_rcp_f32_e32 v191, v191
	v_mul_f32_e32 v92, v92, v184
	v_mul_f32_e32 v93, v93, v185
	v_mul_f32_e32 v94, v94, v186
	v_mul_f32_e32 v95, v95, v187
	v_mul_f32_e32 v88, v88, v188
	v_mul_f32_e32 v89, v89, v189
	v_mul_f32_e32 v90, v90, v190
	v_mul_f32_e32 v91, v91, v191
	v_cvt_pk_bf16_f32 v92, v92, v93
	v_cvt_pk_bf16_f32 v93, v94, v95
	v_cvt_pk_bf16_f32 v94, v88, v89
	v_cvt_pk_bf16_f32 v95, v90, v91
	global_store_dwordx4 v[162:163], v[92:95], off
	v_pk_mul_f32 v[84:85], v[84:85], v[144:145] op_sel_hi:[1,0]
	v_pk_mul_f32 v[86:87], v[86:87], v[144:145] op_sel_hi:[1,0]
	v_pk_mul_f32 v[80:81], v[80:81], v[144:145] op_sel_hi:[1,0]
	v_pk_mul_f32 v[82:83], v[82:83], v[144:145] op_sel_hi:[1,0]
	v_mul_f32_e32 v184, 0xbfb8aa3b, v84
	v_mul_f32_e32 v185, 0xbfb8aa3b, v85
	v_mul_f32_e32 v186, 0xbfb8aa3b, v86
	v_mul_f32_e32 v187, 0xbfb8aa3b, v87
	v_mul_f32_e32 v188, 0xbfb8aa3b, v80
	v_mul_f32_e32 v189, 0xbfb8aa3b, v81
	v_mul_f32_e32 v190, 0xbfb8aa3b, v82
	v_mul_f32_e32 v191, 0xbfb8aa3b, v83
	v_exp_f32_e32 v184, v184
	v_exp_f32_e32 v185, v185
	v_exp_f32_e32 v186, v186
	v_exp_f32_e32 v187, v187
	v_exp_f32_e32 v188, v188
	v_exp_f32_e32 v189, v189
	v_exp_f32_e32 v190, v190
	v_exp_f32_e32 v191, v191
	v_add_f32_e32 v184, 1.0, v184
	v_add_f32_e32 v185, 1.0, v185
	v_add_f32_e32 v186, 1.0, v186
	v_add_f32_e32 v187, 1.0, v187
	v_add_f32_e32 v188, 1.0, v188
	v_add_f32_e32 v189, 1.0, v189
	v_add_f32_e32 v190, 1.0, v190
	v_add_f32_e32 v191, 1.0, v191
	v_rcp_f32_e32 v184, v184
	v_rcp_f32_e32 v185, v185
	v_rcp_f32_e32 v186, v186
	v_rcp_f32_e32 v187, v187
	v_rcp_f32_e32 v188, v188
	v_rcp_f32_e32 v189, v189
	v_rcp_f32_e32 v190, v190
	v_rcp_f32_e32 v191, v191
	v_mul_f32_e32 v84, v84, v184
	v_mul_f32_e32 v85, v85, v185
	v_mul_f32_e32 v86, v86, v186
	v_mul_f32_e32 v87, v87, v187
	v_mul_f32_e32 v80, v80, v188
	v_mul_f32_e32 v81, v81, v189
	v_mul_f32_e32 v82, v82, v190
	v_mul_f32_e32 v83, v83, v191
	v_cvt_pk_bf16_f32 v84, v84, v85
	v_cvt_pk_bf16_f32 v85, v86, v87
	v_cvt_pk_bf16_f32 v86, v80, v81
	v_cvt_pk_bf16_f32 v87, v82, v83
	global_store_dwordx4 v[162:163], v[84:87], off offset:256
	v_lshl_add_u64 v[176:177], v[162:163], 0, s[46:47]
	v_pk_mul_f32 v[76:77], v[76:77], v[146:147] op_sel_hi:[1,0]
	v_pk_mul_f32 v[78:79], v[78:79], v[146:147] op_sel_hi:[1,0]
	v_pk_mul_f32 v[72:73], v[72:73], v[146:147] op_sel_hi:[1,0]
	v_pk_mul_f32 v[74:75], v[74:75], v[146:147] op_sel_hi:[1,0]
	v_mul_f32_e32 v184, 0xbfb8aa3b, v76
	v_mul_f32_e32 v185, 0xbfb8aa3b, v77
	v_mul_f32_e32 v186, 0xbfb8aa3b, v78
	v_mul_f32_e32 v187, 0xbfb8aa3b, v79
	v_mul_f32_e32 v188, 0xbfb8aa3b, v72
	v_mul_f32_e32 v189, 0xbfb8aa3b, v73
	v_mul_f32_e32 v190, 0xbfb8aa3b, v74
	v_mul_f32_e32 v191, 0xbfb8aa3b, v75
	v_exp_f32_e32 v184, v184
	v_exp_f32_e32 v185, v185
	v_exp_f32_e32 v186, v186
	v_exp_f32_e32 v187, v187
	v_exp_f32_e32 v188, v188
	v_exp_f32_e32 v189, v189
	v_exp_f32_e32 v190, v190
	v_exp_f32_e32 v191, v191
	v_add_f32_e32 v184, 1.0, v184
	v_add_f32_e32 v185, 1.0, v185
	v_add_f32_e32 v186, 1.0, v186
	v_add_f32_e32 v187, 1.0, v187
	v_add_f32_e32 v188, 1.0, v188
	v_add_f32_e32 v189, 1.0, v189
	v_add_f32_e32 v190, 1.0, v190
	v_add_f32_e32 v191, 1.0, v191
	v_rcp_f32_e32 v184, v184
	v_rcp_f32_e32 v185, v185
	v_rcp_f32_e32 v186, v186
	v_rcp_f32_e32 v187, v187
	v_rcp_f32_e32 v188, v188
	v_rcp_f32_e32 v189, v189
	v_rcp_f32_e32 v190, v190
	v_rcp_f32_e32 v191, v191
	v_mul_f32_e32 v76, v76, v184
	v_mul_f32_e32 v77, v77, v185
	v_mul_f32_e32 v78, v78, v186
	v_mul_f32_e32 v79, v79, v187
	v_mul_f32_e32 v72, v72, v188
	v_mul_f32_e32 v73, v73, v189
	v_mul_f32_e32 v74, v74, v190
	v_mul_f32_e32 v75, v75, v191
	v_cvt_pk_bf16_f32 v76, v76, v77
	v_cvt_pk_bf16_f32 v77, v78, v79
	v_cvt_pk_bf16_f32 v78, v72, v73
	v_cvt_pk_bf16_f32 v79, v74, v75
	global_store_dwordx4 v[176:177], v[76:79], off
	v_pk_mul_f32 v[68:69], v[68:69], v[146:147] op_sel_hi:[1,0]
	v_pk_mul_f32 v[70:71], v[70:71], v[146:147] op_sel_hi:[1,0]
	v_pk_mul_f32 v[64:65], v[64:65], v[146:147] op_sel_hi:[1,0]
	v_pk_mul_f32 v[66:67], v[66:67], v[146:147] op_sel_hi:[1,0]
	v_mul_f32_e32 v184, 0xbfb8aa3b, v68
	v_mul_f32_e32 v185, 0xbfb8aa3b, v69
	v_mul_f32_e32 v186, 0xbfb8aa3b, v70
	v_mul_f32_e32 v187, 0xbfb8aa3b, v71
	v_mul_f32_e32 v188, 0xbfb8aa3b, v64
	v_mul_f32_e32 v189, 0xbfb8aa3b, v65
	v_mul_f32_e32 v190, 0xbfb8aa3b, v66
	v_mul_f32_e32 v191, 0xbfb8aa3b, v67
	v_exp_f32_e32 v184, v184
	v_exp_f32_e32 v185, v185
	v_exp_f32_e32 v186, v186
	v_exp_f32_e32 v187, v187
	v_exp_f32_e32 v188, v188
	v_exp_f32_e32 v189, v189
	v_exp_f32_e32 v190, v190
	v_exp_f32_e32 v191, v191
	v_add_f32_e32 v184, 1.0, v184
	v_add_f32_e32 v185, 1.0, v185
	v_add_f32_e32 v186, 1.0, v186
	v_add_f32_e32 v187, 1.0, v187
	v_add_f32_e32 v188, 1.0, v188
	v_add_f32_e32 v189, 1.0, v189
	v_add_f32_e32 v190, 1.0, v190
	v_add_f32_e32 v191, 1.0, v191
	v_rcp_f32_e32 v184, v184
	v_rcp_f32_e32 v185, v185
	v_rcp_f32_e32 v186, v186
	v_rcp_f32_e32 v187, v187
	v_rcp_f32_e32 v188, v188
; __device__ __forceinline__ unsigned cvt_pk_bf16(float lo, float hi) { unsigned r; asm volatile("v_cvt_pk_bf16_f32 %0, %1, %2" : "=v"(r) : "v"(lo), "v"(hi)); return r; }
; __device__ __forceinline__ float silu_f(float v) { return v * __builtin_amdgcn_rcpf(1.f + __expf(-v)); }
;     __device__ __forceinline__ void operator()(const f32x4 (&acc)[2][2][4][2], const Unit& u, int wr, int wc, int fr, int fq, int ui, PG8_LAS unsigned char* lds) const {
;     ...
;                 const int row = row0 + ai * HALF + m * 16;
;                 const float rs = rs4[m];
;                 bf16_t* rowp = O + (size_t)row * ldc + col0;
; #pragma unroll
;                 for (int bj = 0; bj < 2; ++bj) {
;                     f32x4 v[2] = {acc[ai][bj][m][0] * rs, acc[ai][bj][m][1] * rs};
;                     if (ksum) { csum[bj][0] += v[0]; csum[bj][1] += v[1]; }
; #pragma unroll
;                     for (int n = 0; n < 2; ++n) {
;                         f32x4 lbv = (f32x4){0.f, 0.f, 0.f, 0.f};
;                         if (act == 2) lbv = *(const f32x4*)(lb + (col0 - 1024) + bj * HALF + 4 * n);
; #pragma unroll
;                         for (int e = 0; e < 4; ++e) {
;                             float x = v[n][e];
;                             if (act == 1) x = silu_f(x);
;                             else if (act == 2) { const float l = lbv[e]; x = __logf(l + (1.f - l) * __builtin_amdgcn_rcpf(1.f + __expf(-x))); }
;                             else if (act == 3) { x = fmaxf(x, 0.f); x = x * x; }
;                             v[n][e] = x;
;                         }
;                     }
;                     u32x4 w; w.x = cvt_pk_bf16(v[0][0], v[0][1]); w.y = cvt_pk_bf16(v[0][2], v[0][3]); w.z = cvt_pk_bf16(v[1][0], v[1][1]); w.w = cvt_pk_bf16(v[1][2], v[1][3]);
;                     *(u32x4*)(rowp + bj * HALF) = w;
	v_rcp_f32_e32 v189, v189
	v_rcp_f32_e32 v190, v190
	v_rcp_f32_e32 v191, v191
	v_mul_f32_e32 v68, v68, v184
	v_mul_f32_e32 v69, v69, v185
	v_mul_f32_e32 v70, v70, v186
	v_mul_f32_e32 v71, v71, v187
	v_mul_f32_e32 v64, v64, v188
	v_mul_f32_e32 v65, v65, v189
	v_mul_f32_e32 v66, v66, v190
	v_mul_f32_e32 v67, v67, v191
	v_cvt_pk_bf16_f32 v68, v68, v69
	v_cvt_pk_bf16_f32 v69, v70, v71
	v_cvt_pk_bf16_f32 v70, v64, v65
	v_cvt_pk_bf16_f32 v71, v66, v67
	global_store_dwordx4 v[176:177], v[68:71], off offset:256
	v_lshl_add_u64 v[162:163], v[178:179], 0, 0
	v_pk_mul_f32 v[60:61], v[60:61], v[148:149] op_sel_hi:[1,0]
	v_pk_mul_f32 v[62:63], v[62:63], v[148:149] op_sel_hi:[1,0]
	v_pk_mul_f32 v[56:57], v[56:57], v[148:149] op_sel_hi:[1,0]
	v_pk_mul_f32 v[58:59], v[58:59], v[148:149] op_sel_hi:[1,0]
	v_mul_f32_e32 v184, 0xbfb8aa3b, v60
	v_mul_f32_e32 v185, 0xbfb8aa3b, v61
	v_mul_f32_e32 v186, 0xbfb8aa3b, v62
	v_mul_f32_e32 v187, 0xbfb8aa3b, v63
	v_mul_f32_e32 v188, 0xbfb8aa3b, v56
	v_mul_f32_e32 v189, 0xbfb8aa3b, v57
	v_mul_f32_e32 v190, 0xbfb8aa3b, v58
	v_mul_f32_e32 v191, 0xbfb8aa3b, v59
	v_exp_f32_e32 v184, v184
	v_exp_f32_e32 v185, v185
	v_exp_f32_e32 v186, v186
	v_exp_f32_e32 v187, v187
	v_exp_f32_e32 v188, v188
	v_exp_f32_e32 v189, v189
	v_exp_f32_e32 v190, v190
	v_exp_f32_e32 v191, v191
	v_add_f32_e32 v184, 1.0, v184
	v_add_f32_e32 v185, 1.0, v185
	v_add_f32_e32 v186, 1.0, v186
	v_add_f32_e32 v187, 1.0, v187
	v_add_f32_e32 v188, 1.0, v188
	v_add_f32_e32 v189, 1.0, v189
	v_add_f32_e32 v190, 1.0, v190
	v_add_f32_e32 v191, 1.0, v191
	v_rcp_f32_e32 v184, v184
	v_rcp_f32_e32 v185, v185
	v_rcp_f32_e32 v186, v186
	v_rcp_f32_e32 v187, v187
	v_rcp_f32_e32 v188, v188
	v_rcp_f32_e32 v189, v189
	v_rcp_f32_e32 v190, v190
	v_rcp_f32_e32 v191, v191
	v_mul_f32_e32 v60, v60, v184
	v_mul_f32_e32 v61, v61, v185
	v_mul_f32_e32 v62, v62, v186
	v_mul_f32_e32 v63, v63, v187
	v_mul_f32_e32 v56, v56, v188
	v_mul_f32_e32 v57, v57, v189
	v_mul_f32_e32 v58, v58, v190
	v_mul_f32_e32 v59, v59, v191
	v_cvt_pk_bf16_f32 v60, v60, v61
	v_cvt_pk_bf16_f32 v61, v62, v63
	v_cvt_pk_bf16_f32 v62, v56, v57
	v_cvt_pk_bf16_f32 v63, v58, v59
	global_store_dwordx4 v[162:163], v[60:63], off
	v_pk_mul_f32 v[52:53], v[52:53], v[148:149] op_sel_hi:[1,0]
	v_pk_mul_f32 v[54:55], v[54:55], v[148:149] op_sel_hi:[1,0]
	v_pk_mul_f32 v[48:49], v[48:49], v[148:149] op_sel_hi:[1,0]
	v_pk_mul_f32 v[50:51], v[50:51], v[148:149] op_sel_hi:[1,0]
	v_mul_f32_e32 v184, 0xbfb8aa3b, v52
	v_mul_f32_e32 v185, 0xbfb8aa3b, v53
	v_mul_f32_e32 v186, 0xbfb8aa3b, v54
	v_mul_f32_e32 v187, 0xbfb8aa3b, v55
	v_mul_f32_e32 v188, 0xbfb8aa3b, v48
	v_mul_f32_e32 v189, 0xbfb8aa3b, v49
	v_mul_f32_e32 v190, 0xbfb8aa3b, v50
	v_mul_f32_e32 v191, 0xbfb8aa3b, v51
	v_exp_f32_e32 v184, v184
	v_exp_f32_e32 v185, v185
	v_exp_f32_e32 v186, v186
	v_exp_f32_e32 v187, v187
	v_exp_f32_e32 v188, v188
	v_exp_f32_e32 v189, v189
	v_exp_f32_e32 v190, v190
	v_exp_f32_e32 v191, v191
	v_add_f32_e32 v184, 1.0, v184
	v_add_f32_e32 v185, 1.0, v185
	v_add_f32_e32 v186, 1.0, v186
	v_add_f32_e32 v187, 1.0, v187
	v_add_f32_e32 v188, 1.0, v188
	v_add_f32_e32 v189, 1.0, v189
	v_add_f32_e32 v190, 1.0, v190
	v_add_f32_e32 v191, 1.0, v191
	v_rcp_f32_e32 v184, v184
	v_rcp_f32_e32 v185, v185
	v_rcp_f32_e32 v186, v186
	v_rcp_f32_e32 v187, v187
	v_rcp_f32_e32 v188, v188
	v_rcp_f32_e32 v189, v189
	v_rcp_f32_e32 v190, v190
	v_rcp_f32_e32 v191, v191
	v_mul_f32_e32 v52, v52, v184
	v_mul_f32_e32 v53, v53, v185
	v_mul_f32_e32 v54, v54, v186
	v_mul_f32_e32 v55, v55, v187
	v_mul_f32_e32 v48, v48, v188
	v_mul_f32_e32 v49, v49, v189
	v_mul_f32_e32 v50, v50, v190
	v_mul_f32_e32 v51, v51, v191
	v_cvt_pk_bf16_f32 v52, v52, v53
	v_cvt_pk_bf16_f32 v53, v54, v55
	v_cvt_pk_bf16_f32 v54, v48, v49
	v_cvt_pk_bf16_f32 v55, v50, v51
	global_store_dwordx4 v[162:163], v[52:55], off offset:256
	v_lshl_add_u64 v[176:177], v[162:163], 0, s[46:47]
	v_pk_mul_f32 v[44:45], v[44:45], v[156:157] op_sel_hi:[1,0]
	v_pk_mul_f32 v[46:47], v[46:47], v[156:157] op_sel_hi:[1,0]
	v_pk_mul_f32 v[40:41], v[40:41], v[156:157] op_sel_hi:[1,0]
	v_pk_mul_f32 v[42:43], v[42:43], v[156:157] op_sel_hi:[1,0]
	v_mul_f32_e32 v184, 0xbfb8aa3b, v44
	v_mul_f32_e32 v185, 0xbfb8aa3b, v45
	v_mul_f32_e32 v186, 0xbfb8aa3b, v46
	v_mul_f32_e32 v187, 0xbfb8aa3b, v47
	v_mul_f32_e32 v188, 0xbfb8aa3b, v40
	v_mul_f32_e32 v189, 0xbfb8aa3b, v41
	v_mul_f32_e32 v190, 0xbfb8aa3b, v42
	v_mul_f32_e32 v191, 0xbfb8aa3b, v43
	v_exp_f32_e32 v184, v184
	v_exp_f32_e32 v185, v185
	v_exp_f32_e32 v186, v186
	v_exp_f32_e32 v187, v187
	v_exp_f32_e32 v188, v188
	v_exp_f32_e32 v189, v189
	v_exp_f32_e32 v190, v190
	v_exp_f32_e32 v191, v191
	v_add_f32_e32 v184, 1.0, v184
	v_add_f32_e32 v185, 1.0, v185
	v_add_f32_e32 v186, 1.0, v186
	v_add_f32_e32 v187, 1.0, v187
	v_add_f32_e32 v188, 1.0, v188
	v_add_f32_e32 v189, 1.0, v189
	v_add_f32_e32 v190, 1.0, v190
	v_add_f32_e32 v191, 1.0, v191
	v_rcp_f32_e32 v184, v184
	v_rcp_f32_e32 v185, v185
	v_rcp_f32_e32 v186, v186
	v_rcp_f32_e32 v187, v187
	v_rcp_f32_e32 v188, v188
	v_rcp_f32_e32 v189, v189
	v_rcp_f32_e32 v190, v190
	v_rcp_f32_e32 v191, v191
	v_mul_f32_e32 v44, v44, v184
	v_mul_f32_e32 v45, v45, v185
	v_mul_f32_e32 v46, v46, v186
	v_mul_f32_e32 v47, v47, v187
	v_mul_f32_e32 v40, v40, v188
	v_mul_f32_e32 v41, v41, v189
	v_mul_f32_e32 v42, v42, v190
	v_mul_f32_e32 v43, v43, v191
	v_cvt_pk_bf16_f32 v44, v44, v45
	v_cvt_pk_bf16_f32 v45, v46, v47
	v_cvt_pk_bf16_f32 v46, v40, v41
	v_cvt_pk_bf16_f32 v47, v42, v43
	global_store_dwordx4 v[176:177], v[44:47], off
	v_pk_mul_f32 v[36:37], v[36:37], v[156:157] op_sel_hi:[1,0]
	v_pk_mul_f32 v[38:39], v[38:39], v[156:157] op_sel_hi:[1,0]
; __device__ __forceinline__ unsigned cvt_pk_bf16(float lo, float hi) { unsigned r; asm volatile("v_cvt_pk_bf16_f32 %0, %1, %2" : "=v"(r) : "v"(lo), "v"(hi)); return r; }
; __device__ __forceinline__ float silu_f(float v) { return v * __builtin_amdgcn_rcpf(1.f + __expf(-v)); }
;     __device__ __forceinline__ void operator()(const f32x4 (&acc)[2][2][4][2], const Unit& u, int wr, int wc, int fr, int fq, int ui, PG8_LAS unsigned char* lds) const {
;     ...
;                 const int row = row0 + ai * HALF + m * 16;
;                 const float rs = rs4[m];
;                 bf16_t* rowp = O + (size_t)row * ldc + col0;
; #pragma unroll
;                 for (int bj = 0; bj < 2; ++bj) {
;                     f32x4 v[2] = {acc[ai][bj][m][0] * rs, acc[ai][bj][m][1] * rs};
;                     if (ksum) { csum[bj][0] += v[0]; csum[bj][1] += v[1]; }
; #pragma unroll
;                     for (int n = 0; n < 2; ++n) {
;                         f32x4 lbv = (f32x4){0.f, 0.f, 0.f, 0.f};
;                         if (act == 2) lbv = *(const f32x4*)(lb + (col0 - 1024) + bj * HALF + 4 * n);
; #pragma unroll
;                         for (int e = 0; e < 4; ++e) {
;                             float x = v[n][e];
;                             if (act == 1) x = silu_f(x);
;                             else if (act == 2) { const float l = lbv[e]; x = __logf(l + (1.f - l) * __builtin_amdgcn_rcpf(1.f + __expf(-x))); }
;                             else if (act == 3) { x = fmaxf(x, 0.f); x = x * x; }
;                             v[n][e] = x;
;                         }
;                     }
;                     u32x4 w; w.x = cvt_pk_bf16(v[0][0], v[0][1]); w.y = cvt_pk_bf16(v[0][2], v[0][3]); w.z = cvt_pk_bf16(v[1][0], v[1][1]); w.w = cvt_pk_bf16(v[1][2], v[1][3]);
;                     *(u32x4*)(rowp + bj * HALF) = w;
	v_pk_mul_f32 v[32:33], v[32:33], v[156:157] op_sel_hi:[1,0]
	v_pk_mul_f32 v[34:35], v[34:35], v[156:157] op_sel_hi:[1,0]
	v_mul_f32_e32 v184, 0xbfb8aa3b, v36
	v_mul_f32_e32 v185, 0xbfb8aa3b, v37
	v_mul_f32_e32 v186, 0xbfb8aa3b, v38
	v_mul_f32_e32 v187, 0xbfb8aa3b, v39
	v_mul_f32_e32 v188, 0xbfb8aa3b, v32
	v_mul_f32_e32 v189, 0xbfb8aa3b, v33
	v_mul_f32_e32 v190, 0xbfb8aa3b, v34
	v_mul_f32_e32 v191, 0xbfb8aa3b, v35
	v_exp_f32_e32 v184, v184
	v_exp_f32_e32 v185, v185
	v_exp_f32_e32 v186, v186
	v_exp_f32_e32 v187, v187
	v_exp_f32_e32 v188, v188
	v_exp_f32_e32 v189, v189
	v_exp_f32_e32 v190, v190
	v_exp_f32_e32 v191, v191
	v_add_f32_e32 v184, 1.0, v184
	v_add_f32_e32 v185, 1.0, v185
	v_add_f32_e32 v186, 1.0, v186
	v_add_f32_e32 v187, 1.0, v187
	v_add_f32_e32 v188, 1.0, v188
	v_add_f32_e32 v189, 1.0, v189
	v_add_f32_e32 v190, 1.0, v190
	v_add_f32_e32 v191, 1.0, v191
	v_rcp_f32_e32 v184, v184
	v_rcp_f32_e32 v185, v185
	v_rcp_f32_e32 v186, v186
	v_rcp_f32_e32 v187, v187
	v_rcp_f32_e32 v188, v188
	v_rcp_f32_e32 v189, v189
	v_rcp_f32_e32 v190, v190
	v_rcp_f32_e32 v191, v191
	v_mul_f32_e32 v36, v36, v184
	v_mul_f32_e32 v37, v37, v185
	v_mul_f32_e32 v38, v38, v186
	v_mul_f32_e32 v39, v39, v187
	v_mul_f32_e32 v32, v32, v188
	v_mul_f32_e32 v33, v33, v189
	v_mul_f32_e32 v34, v34, v190
	v_mul_f32_e32 v35, v35, v191
	v_cvt_pk_bf16_f32 v36, v36, v37
	v_cvt_pk_bf16_f32 v37, v38, v39
	v_cvt_pk_bf16_f32 v38, v32, v33
	v_cvt_pk_bf16_f32 v39, v34, v35
	global_store_dwordx4 v[176:177], v[36:39], off offset:256
	v_lshl_add_u64 v[162:163], v[176:177], 0, s[46:47]
	v_pk_mul_f32 v[28:29], v[28:29], v[158:159] op_sel_hi:[1,0]
	v_pk_mul_f32 v[30:31], v[30:31], v[158:159] op_sel_hi:[1,0]
	v_pk_mul_f32 v[24:25], v[24:25], v[158:159] op_sel_hi:[1,0]
	v_pk_mul_f32 v[26:27], v[26:27], v[158:159] op_sel_hi:[1,0]
	v_mul_f32_e32 v184, 0xbfb8aa3b, v28
	v_mul_f32_e32 v185, 0xbfb8aa3b, v29
	v_mul_f32_e32 v186, 0xbfb8aa3b, v30
	v_mul_f32_e32 v187, 0xbfb8aa3b, v31
	v_mul_f32_e32 v188, 0xbfb8aa3b, v24
	v_mul_f32_e32 v189, 0xbfb8aa3b, v25
	v_mul_f32_e32 v190, 0xbfb8aa3b, v26
	v_mul_f32_e32 v191, 0xbfb8aa3b, v27
	v_exp_f32_e32 v184, v184
	v_exp_f32_e32 v185, v185
	v_exp_f32_e32 v186, v186
	v_exp_f32_e32 v187, v187
	v_exp_f32_e32 v188, v188
	v_exp_f32_e32 v189, v189
	v_exp_f32_e32 v190, v190
	v_exp_f32_e32 v191, v191
	v_add_f32_e32 v184, 1.0, v184
	v_add_f32_e32 v185, 1.0, v185
	v_add_f32_e32 v186, 1.0, v186
	v_add_f32_e32 v187, 1.0, v187
	v_add_f32_e32 v188, 1.0, v188
	v_add_f32_e32 v189, 1.0, v189
	v_add_f32_e32 v190, 1.0, v190
	v_add_f32_e32 v191, 1.0, v191
	v_rcp_f32_e32 v184, v184
	v_rcp_f32_e32 v185, v185
	v_rcp_f32_e32 v186, v186
	v_rcp_f32_e32 v187, v187
	v_rcp_f32_e32 v188, v188
	v_rcp_f32_e32 v189, v189
	v_rcp_f32_e32 v190, v190
	v_rcp_f32_e32 v191, v191
	v_mul_f32_e32 v28, v28, v184
	v_mul_f32_e32 v29, v29, v185
	v_mul_f32_e32 v30, v30, v186
	v_mul_f32_e32 v31, v31, v187
	v_mul_f32_e32 v24, v24, v188
	v_mul_f32_e32 v25, v25, v189
	v_mul_f32_e32 v26, v26, v190
	v_mul_f32_e32 v27, v27, v191
	v_cvt_pk_bf16_f32 v28, v28, v29
	v_cvt_pk_bf16_f32 v29, v30, v31
	v_cvt_pk_bf16_f32 v30, v24, v25
	v_cvt_pk_bf16_f32 v31, v26, v27
	global_store_dwordx4 v[162:163], v[28:31], off
	v_pk_mul_f32 v[20:21], v[20:21], v[158:159] op_sel_hi:[1,0]
	v_pk_mul_f32 v[22:23], v[22:23], v[158:159] op_sel_hi:[1,0]
	v_pk_mul_f32 v[16:17], v[16:17], v[158:159] op_sel_hi:[1,0]
	v_pk_mul_f32 v[18:19], v[18:19], v[158:159] op_sel_hi:[1,0]
	v_mul_f32_e32 v184, 0xbfb8aa3b, v20
	v_mul_f32_e32 v185, 0xbfb8aa3b, v21
	v_mul_f32_e32 v186, 0xbfb8aa3b, v22
	v_mul_f32_e32 v187, 0xbfb8aa3b, v23
	v_mul_f32_e32 v188, 0xbfb8aa3b, v16
	v_mul_f32_e32 v189, 0xbfb8aa3b, v17
	v_mul_f32_e32 v190, 0xbfb8aa3b, v18
	v_mul_f32_e32 v191, 0xbfb8aa3b, v19
	v_exp_f32_e32 v184, v184
	v_exp_f32_e32 v185, v185
	v_exp_f32_e32 v186, v186
	v_exp_f32_e32 v187, v187
	v_exp_f32_e32 v188, v188
	v_exp_f32_e32 v189, v189
	v_exp_f32_e32 v190, v190
	v_exp_f32_e32 v191, v191
	v_add_f32_e32 v184, 1.0, v184
	v_add_f32_e32 v185, 1.0, v185
	v_add_f32_e32 v186, 1.0, v186
; __device__ __forceinline__ unsigned cvt_pk_bf16(float lo, float hi) { unsigned r; asm volatile("v_cvt_pk_bf16_f32 %0, %1, %2" : "=v"(r) : "v"(lo), "v"(hi)); return r; }
; __device__ __forceinline__ float silu_f(float v) { return v * __builtin_amdgcn_rcpf(1.f + __expf(-v)); }
;     __device__ __forceinline__ void operator()(const f32x4 (&acc)[2][2][4][2], const Unit& u, int wr, int wc, int fr, int fq, int ui, PG8_LAS unsigned char* lds) const {
;     ...
;                 const int row = row0 + ai * HALF + m * 16;
;                 const float rs = rs4[m];
;                 bf16_t* rowp = O + (size_t)row * ldc + col0;
; #pragma unroll
;                 for (int bj = 0; bj < 2; ++bj) {
;                     f32x4 v[2] = {acc[ai][bj][m][0] * rs, acc[ai][bj][m][1] * rs};
;                     if (ksum) { csum[bj][0] += v[0]; csum[bj][1] += v[1]; }
; #pragma unroll
;                     for (int n = 0; n < 2; ++n) {
;                         f32x4 lbv = (f32x4){0.f, 0.f, 0.f, 0.f};
;                         if (act == 2) lbv = *(const f32x4*)(lb + (col0 - 1024) + bj * HALF + 4 * n);
; #pragma unroll
;                         for (int e = 0; e < 4; ++e) {
;                             float x = v[n][e];
;                             if (act == 1) x = silu_f(x);
;                             else if (act == 2) { const float l = lbv[e]; x = __logf(l + (1.f - l) * __builtin_amdgcn_rcpf(1.f + __expf(-x))); }
;                             else if (act == 3) { x = fmaxf(x, 0.f); x = x * x; }
;                             v[n][e] = x;
;                         }
;                     }
;                     u32x4 w; w.x = cvt_pk_bf16(v[0][0], v[0][1]); w.y = cvt_pk_bf16(v[0][2], v[0][3]); w.z = cvt_pk_bf16(v[1][0], v[1][1]); w.w = cvt_pk_bf16(v[1][2], v[1][3]);
;                     *(u32x4*)(rowp + bj * HALF) = w;
	v_add_f32_e32 v187, 1.0, v187
	v_add_f32_e32 v188, 1.0, v188
	v_add_f32_e32 v189, 1.0, v189
	v_add_f32_e32 v190, 1.0, v190
	v_add_f32_e32 v191, 1.0, v191
	v_rcp_f32_e32 v184, v184
	v_rcp_f32_e32 v185, v185
	v_rcp_f32_e32 v186, v186
	v_rcp_f32_e32 v187, v187
	v_rcp_f32_e32 v188, v188
	v_rcp_f32_e32 v189, v189
	v_rcp_f32_e32 v190, v190
	v_rcp_f32_e32 v191, v191
	v_mul_f32_e32 v20, v20, v184
	v_mul_f32_e32 v21, v21, v185
	v_mul_f32_e32 v22, v22, v186
	v_mul_f32_e32 v23, v23, v187
	v_mul_f32_e32 v16, v16, v188
	v_mul_f32_e32 v17, v17, v189
	v_mul_f32_e32 v18, v18, v190
	v_mul_f32_e32 v19, v19, v191
	v_cvt_pk_bf16_f32 v20, v20, v21
	v_cvt_pk_bf16_f32 v21, v22, v23
	v_cvt_pk_bf16_f32 v22, v16, v17
	v_cvt_pk_bf16_f32 v23, v18, v19
	global_store_dwordx4 v[162:163], v[20:23], off offset:256
	v_lshl_add_u64 v[176:177], v[162:163], 0, s[46:47]
	v_pk_mul_f32 v[12:13], v[12:13], v[160:161] op_sel_hi:[1,0]
	v_pk_mul_f32 v[14:15], v[14:15], v[160:161] op_sel_hi:[1,0]
	v_pk_mul_f32 v[8:9], v[8:9], v[160:161] op_sel_hi:[1,0]
	v_pk_mul_f32 v[10:11], v[10:11], v[160:161] op_sel_hi:[1,0]
	v_mul_f32_e32 v184, 0xbfb8aa3b, v12
	v_mul_f32_e32 v185, 0xbfb8aa3b, v13
	v_mul_f32_e32 v186, 0xbfb8aa3b, v14
	v_mul_f32_e32 v187, 0xbfb8aa3b, v15
	v_mul_f32_e32 v188, 0xbfb8aa3b, v8
	v_mul_f32_e32 v189, 0xbfb8aa3b, v9
	v_mul_f32_e32 v190, 0xbfb8aa3b, v10
	v_mul_f32_e32 v191, 0xbfb8aa3b, v11
	v_exp_f32_e32 v184, v184
	v_exp_f32_e32 v185, v185
	v_exp_f32_e32 v186, v186
	v_exp_f32_e32 v187, v187
	v_exp_f32_e32 v188, v188
	v_exp_f32_e32 v189, v189
	v_exp_f32_e32 v190, v190
	v_exp_f32_e32 v191, v191
	v_add_f32_e32 v184, 1.0, v184
	v_add_f32_e32 v185, 1.0, v185
	v_add_f32_e32 v186, 1.0, v186
	v_add_f32_e32 v187, 1.0, v187
	v_add_f32_e32 v188, 1.0, v188
	v_add_f32_e32 v189, 1.0, v189
	v_add_f32_e32 v190, 1.0, v190
	v_add_f32_e32 v191, 1.0, v191
	v_rcp_f32_e32 v184, v184
	v_rcp_f32_e32 v185, v185
	v_rcp_f32_e32 v186, v186
	v_rcp_f32_e32 v187, v187
	v_rcp_f32_e32 v188, v188
	v_rcp_f32_e32 v189, v189
	v_rcp_f32_e32 v190, v190
	v_rcp_f32_e32 v191, v191
	v_mul_f32_e32 v12, v12, v184
	v_mul_f32_e32 v13, v13, v185
	v_mul_f32_e32 v14, v14, v186
	v_mul_f32_e32 v15, v15, v187
	v_mul_f32_e32 v8, v8, v188
	v_mul_f32_e32 v9, v9, v189
	v_mul_f32_e32 v10, v10, v190
	v_mul_f32_e32 v11, v11, v191
	v_cvt_pk_bf16_f32 v12, v12, v13
	v_cvt_pk_bf16_f32 v13, v14, v15
	v_cvt_pk_bf16_f32 v14, v8, v9
	v_cvt_pk_bf16_f32 v15, v10, v11
	global_store_dwordx4 v[176:177], v[12:15], off
	v_pk_mul_f32 v[4:5], v[4:5], v[160:161] op_sel_hi:[1,0]
	v_pk_mul_f32 v[6:7], v[6:7], v[160:161] op_sel_hi:[1,0]
	v_pk_mul_f32 v[0:1], v[0:1], v[160:161] op_sel_hi:[1,0]
	v_pk_mul_f32 v[2:3], v[2:3], v[160:161] op_sel_hi:[1,0]
	v_mul_f32_e32 v184, 0xbfb8aa3b, v4
	v_mul_f32_e32 v185, 0xbfb8aa3b, v5
	v_mul_f32_e32 v186, 0xbfb8aa3b, v6
	v_mul_f32_e32 v187, 0xbfb8aa3b, v7
	v_mul_f32_e32 v188, 0xbfb8aa3b, v0
	v_mul_f32_e32 v189, 0xbfb8aa3b, v1
	v_mul_f32_e32 v190, 0xbfb8aa3b, v2
	v_mul_f32_e32 v191, 0xbfb8aa3b, v3
	v_exp_f32_e32 v184, v184
	v_exp_f32_e32 v185, v185
	v_exp_f32_e32 v186, v186
	v_exp_f32_e32 v187, v187
	v_exp_f32_e32 v188, v188
	v_exp_f32_e32 v189, v189
	v_exp_f32_e32 v190, v190
	v_exp_f32_e32 v191, v191
	v_add_f32_e32 v184, 1.0, v184
	v_add_f32_e32 v185, 1.0, v185
	v_add_f32_e32 v186, 1.0, v186
	v_add_f32_e32 v187, 1.0, v187
	v_add_f32_e32 v188, 1.0, v188
	v_add_f32_e32 v189, 1.0, v189
	v_add_f32_e32 v190, 1.0, v190
	v_add_f32_e32 v191, 1.0, v191
	v_rcp_f32_e32 v184, v184
	v_rcp_f32_e32 v185, v185
	v_rcp_f32_e32 v186, v186
	v_rcp_f32_e32 v187, v187
	v_rcp_f32_e32 v188, v188
	v_rcp_f32_e32 v189, v189
	v_rcp_f32_e32 v190, v190
	v_rcp_f32_e32 v191, v191
	v_mul_f32_e32 v4, v4, v184
	v_mul_f32_e32 v5, v5, v185
	v_mul_f32_e32 v6, v6, v186
	v_mul_f32_e32 v7, v7, v187
	v_mul_f32_e32 v0, v0, v188
	v_mul_f32_e32 v1, v1, v189
	v_mul_f32_e32 v2, v2, v190
	v_mul_f32_e32 v3, v3, v191
	v_cvt_pk_bf16_f32 v4, v4, v5
	v_cvt_pk_bf16_f32 v5, v6, v7
	v_cvt_pk_bf16_f32 v6, v0, v1
	v_cvt_pk_bf16_f32 v7, v2, v3
	global_store_dwordx4 v[176:177], v[4:7], off offset:256
	s_branch .LBB0_1108
